# P2a: each dil CU takes three consecutive query blocks of one (b,g,head) instead of items 128 apart (K/V row reuse)
# baseline (speedup 1.0000x reference)
; __global__ void __launch_bounds__(512, 2) fwd_megakernel(Params p) {
;     ...
;     for (int rep = 0; rep < REP_P2A; ++rep) {
;     if (rep) xcd_barrier(xb);
;     for (int it = bid; it < 128 + 384; it += G) {
;       if (it < 128) { for (int q = 0; q < REP_CMP; ++q) compress_item(p, l, it, smem); }
;       else { for (int q = 0; q < REP_DIL; ++q) dil_item(p, it - 128, smem); }
.LBB0_260:
	s_or_b64 exec, exec, s[0:1]
	v_readlane_b32 s0, v254, 46
	v_readlane_b32 s1, v254, 47
	s_andn2_b64 vcc, exec, s[0:1]
	v_readlane_b32 s0, v255, 31
	v_readlane_b32 s1, v255, 32
	s_mov_b32 s1, s88
	v_writelane_b32 v255, s0, 31
	s_waitcnt lgkmcnt(0)
	s_barrier
	v_writelane_b32 v255, s1, 32
	s_cbranch_vccnz .LBB0_332
	v_readlane_b32 s0, v255, 31
	v_readlane_b32 s1, v255, 32
	s_lshl_b64 s[6:7], s[0:1], 1
	s_lshl_b64 s[0:1], s[0:1], 10
	s_add_u32 s8, s64, s0
	s_addc_u32 s9, s65, s1
	v_readlane_b32 s13, v253, 21
	v_readlane_b32 s0, v253, 12
	s_nop 1
	s_cmpk_lg_u32 s0, 0x100
	s_cbranch_scc1 .LBB0_265
	s_cmpk_lt_i32 s13, 0x80
	s_cbranch_scc1 .LBB0_265
	s_sub_i32 s0, s13, 0x80
	s_mul_i32 s0, s0, 3
	s_add_i32 s13, s0, 0x80
	s_branch .LBB0_265

; __global__ void __launch_bounds__(512, 2) fwd_megakernel(Params p) {
;     ...
;     for (int it = bid; it < 128 + 384; it += G) {
.LBB0_264:
	v_readlane_b32 s0, v253, 12
	s_nop 1
	s_cmpk_lg_u32 s0, 0x100
	s_cbranch_scc1 .Lp2a_generic
	s_cmpk_lt_i32 s13, 0x80
	s_cbranch_scc1 .LBB0_332
	s_add_i32 s13, s13, 1
	s_sub_i32 s0, s13, 0x80
	s_mul_i32 s1, s0, 0xaaab
	s_lshr_b32 s1, s1, 17
	s_mul_i32 s1, s1, 3
	s_cmp_eq_u32 s1, s0
	s_cbranch_scc1 .LBB0_332
	s_branch .LBB0_265
